# placement experiment: whole kernel body shifted by 4 bytes (one unexecuted s_nop near the start), so the five GEMM loop heads that sat at 4 mod 8 now sit at 0 mod 8
# speedup vs baseline: 1.0015x; 1.0015x over previous
; __device__ __forceinline__ void phase_prep(const Params& p, u16* sm) {
;   const int tid = threadIdx.x & 255, sub = threadIdx.x >> 8;
;   sm += sub * 2 * 64 * LDSP;
;   const int n_tr = (768 + 256 + 512 + 256 + 1408 * 2 + 704 * 2 + 64 * 2 + 2 * 2) / 2;
;   const int n_rope = NTOK * 32 / 256;
;   const int n_bias = 64;
;   const int n_norm = NTOK / 8;
;   const int total = n_tr + n_rope + n_bias + n_norm;
;   for (int i = blockIdx.x * NTHR + threadIdx.x; i < 4 * NTOK; i += gridDim.x * NTHR) p.rowss[i] = 0ull;
;   for (int it = 2 * blockIdx.x + sub; it < total; it += 2 * gridDim.x) {
;     if (it < n_tr) {
;       const int tl = it * 2;
;       constexpr int T1 = 768, T2 = T1 + 256, T3 = T2 + 512, T4 = T3 + 256, T5 = T4 + 1408, T6 = T5 + 1408,
;                     T7 = T6 + 704, T8 = T7 + 704, T9 = T8 + 64, T10 = T9 + 64, T11 = T10 + 2;
;       if (tl < T1) { transpose_tile2(p.sba_w_in, p.wt_sba_in, 1024, 3072, 3072, tl - (0), sm); }
;       else if (tl < T2) { transpose_tile2(p.sba_w_out, p.wt_sba_out, 1024, 1024, 1024, tl - (T1), sm); }
;       else if (tl < T3) {
;         const int nt0 = (tl - T2) & 31, nt1 = nt0 + 1;
;         const bool rp0 = (nt0 < 16) || (nt0 == 20) || (nt0 == 21) || (nt0 == 24) || (nt0 == 25);
;         const bool rp1 = (nt1 < 16) || (nt1 == 20) || (nt1 == 21) || (nt1 == 24) || (nt1 == 25);
;         transpose_tile2(p.nsa_w_in, p.wt_nsa_in, 1024, 1840, NSAWP, tl - (T2), sm, rp0, rp1, false, p.norm_mix + DM);
;       }
;       else if (tl < T4) { transpose_tile2(p.nsa_w_out, p.wt_nsa_out, 1024, 1024, 1024, tl - (T3), sm); }
;       else if (tl < T5) { transpose_tile2(p.w_up, p.wt_up0, 1024, NUP, NUP, tl - (T4), sm, false, false, true, p.norm_ffn); }
;       else if (tl < T6) { transpose_tile2(p.w_up + (size_t)1024 * NUP, p.wt_up1, 1024, NUP, NUP, tl - (T5), sm, false, false, true, p.norm_ffn + DM); }
;       else if (tl < T7) { transpose_tile2(p.w_down, p.wt_down0, DFF, 1024, 1024, tl - (T6), sm); }
;       else if (tl < T8) { transpose_tile2(p.w_down + (size_t)DFF * 1024, p.wt_down1, DFF, 1024, 1024, tl - (T7), sm); }
;       else if (tl < T9) { transpose_tile2(p.ck_w1, p.wt_ck1, 2048, 128, 128, tl - (T8), sm); }
;       else if (tl < T10) { transpose_tile2(p.cv_w1, p.wt_cv1, 2048, 128, 128, tl - (T9), sm); }
;       else if (tl < T11) { transpose_tile2(p.ck_w2, p.wt_ck2, 128, 64, 64, tl - (T10), sm); }
.LBB0_7:
	v_writelane_b32 v253, s84, 46
	s_nop 1
	v_writelane_b32 v253, s85, 47
	s_or_b64 exec, exec, s[4:5]
	v_lshrrev_b32_e32 v3, 8, v192
	v_lshl_add_u32 v1, s2, 1, v3
	s_movk_i32 s0, 0x2c42
	s_mov_b64 s[90:91], s[42:43]
	s_mov_b64 s[36:37], s[96:97]
	v_cmp_gt_i32_e32 vcc, s0, v1
	s_and_saveexec_b64 s[10:11], vcc
	s_cbranch_execz .LBB0_243
	v_and_b32_e32 v10, 31, v192
	v_cvt_f32_ubyte0_e32 v10, v10
	v_mul_f32_e32 v24, 0xbd000000, v10
	s_movk_i32 s3, 0x7f
	v_mov_b32_e32 v10, 0x461c4000
	v_cmp_eq_f32_e32 vcc, 0, v24
	v_cmp_gt_u32_sdwa s[4:5], v192, s3 src0_sel:BYTE_0 src1_sel:DWORD
	s_mov_b32 s3, 0x3f2aaaab
	v_cndmask_b32_e64 v20, v10, 1.0, vcc
	v_writelane_b32 v253, s4, 42
	v_frexp_mant_f32_e32 v10, v20
	s_mov_b32 s7, 0x42b17218
	v_writelane_b32 v253, s5, 43
	v_cmp_gt_f32_e64 s[4:5], s3, v10
	s_mov_b32 s3, 0x3f317218
	s_mov_b32 s6, 0x7f800000
	v_cndmask_b32_e64 v11, 1.0, 2.0, s[4:5]
	v_mul_f32_e32 v10, v10, v11
	v_add_f32_e32 v13, 1.0, v10
	v_rcp_f32_e32 v18, v13
	v_add_f32_e32 v11, -1.0, v13
	v_sub_f32_e32 v15, v10, v11
	v_add_f32_e32 v11, -1.0, v10
	v_mul_f32_e32 v19, v11, v18
	v_mul_f32_e32 v12, v13, v19
	v_fma_f32 v14, v19, v13, -v12
	v_fmac_f32_e32 v14, v19, v15
	v_add_f32_e32 v10, v12, v14
	v_sub_f32_e32 v13, v11, v10
	v_pk_add_f32 v[16:17], v[10:11], v[12:13] neg_lo:[0,1] neg_hi:[0,1]
	v_mov_b32_e32 v15, v10
	v_pk_add_f32 v[10:11], v[16:17], v[14:15] neg_lo:[0,1] neg_hi:[0,1]
	v_mov_b32_e32 v14, 0x3e91f4c4
	v_add_f32_e32 v10, v10, v11
	v_add_f32_e32 v10, v13, v10
	v_mul_f32_e32 v11, v18, v10
	v_add_f32_e32 v10, v19, v11
	v_sub_f32_e32 v12, v10, v19
	v_sub_f32_e32 v21, v11, v12
	v_mul_f32_e32 v11, v10, v10
	v_fma_f32 v13, v10, v10, -v11
	v_add_f32_e32 v12, v21, v21
	v_fmac_f32_e32 v13, v10, v12
	v_add_f32_e32 v12, v11, v13
	v_fmac_f32_e32 v14, 0x3e76c4e1, v12
	v_fmaak_f32 v14, v12, v14, 0x3ecccdef
	v_sub_f32_e32 v11, v12, v11
	v_sub_f32_e32 v22, v13, v11
	v_mul_f32_e32 v11, v12, v14
	v_fma_f32 v13, v12, v14, -v11
	v_fmac_f32_e32 v13, v22, v14
	v_add_f32_e32 v14, v11, v13
	v_add_f32_e32 v15, 0x3f2aaaaa, v14
	v_sub_f32_e32 v11, v14, v11
	v_sub_f32_e32 v11, v13, v11
	v_add_f32_e32 v13, 0xbf2aaaaa, v15
	v_add_f32_e32 v11, 0x31739010, v11
	v_sub_f32_e32 v13, v14, v13
	v_pk_mul_f32 v[16:17], v[10:11], v[12:13]
	v_pk_add_f32 v[18:19], v[10:11], v[12:13]
	v_fma_f32 v14, v12, v10, -v16
	v_fmac_f32_e32 v14, v12, v21
	v_mov_b32_e32 v17, v19
	v_fmac_f32_e32 v14, v22, v10
	v_pk_add_f32 v[12:13], v[16:17], v[14:15]
	v_ldexp_f32 v22, v21, 1
	v_sub_f32_e32 v11, v12, v16
	v_sub_f32_e32 v11, v14, v11
	v_sub_f32_e32 v14, v15, v13
	v_add_f32_e32 v17, v19, v14
	v_pk_mul_f32 v[14:15], v[12:13], v[12:13] op_sel:[0,1] op_sel_hi:[1,0]
	v_cvt_f64_f32_e32 v[18:19], v20
	v_frexp_exp_i32_f64_e32 v15, v[18:19]
	v_subbrev_co_u32_e64 v15, s[4:5], 0, v15, s[4:5]
	v_cvt_f32_i32_e32 v15, v15
	v_fma_f32 v16, v12, v13, -v14
	v_fmac_f32_e32 v16, v12, v17
	v_fmac_f32_e32 v16, v11, v13
	v_mul_f32_e32 v12, 0x3f317218, v15
	v_fma_f32 v11, v15, s3, -v12
	v_fmamk_f32 v18, v15, 0xb102e308, v11
	v_ldexp_f32 v19, v10, 1
	v_add_f32_e32 v13, v14, v16
	v_pk_add_f32 v[10:11], v[12:13], v[18:19]
	v_mov_b32_e32 v20, v13
	v_mov_b32_e32 v21, v11
	v_mov_b32_e32 v15, v19
	v_pk_add_f32 v[14:15], v[20:21], v[14:15] neg_lo:[0,1] neg_hi:[0,1]
	v_mov_b32_e32 v17, v13
	v_pk_add_f32 v[14:15], v[16:17], v[14:15] neg_lo:[0,1] neg_hi:[0,1]
	v_mov_b32_e32 v19, v10
	v_add_f32_e32 v13, v22, v14
	v_add_f32_e32 v13, v13, v15
	v_pk_add_f32 v[14:15], v[10:11], v[12:13] neg_lo:[0,1] neg_hi:[0,1]
	v_pk_add_f32 v[16:17], v[10:11], v[12:13]
	v_mov_b32_e32 v12, v13
	v_mov_b32_e32 v15, v17
	v_pk_add_f32 v[20:21], v[18:19], v[14:15] neg_lo:[0,1] neg_hi:[0,1]
	v_pk_add_f32 v[14:15], v[18:19], v[14:15]
	v_mov_b32_e32 v13, v10
	v_pk_add_f32 v[18:19], v[14:15], v[10:11] op_sel:[1,0] op_sel_hi:[0,1] neg_lo:[0,1] neg_hi:[0,1]
	v_pk_add_f32 v[22:23], v[16:17], v[18:19] op_sel_hi:[1,0] neg_lo:[0,1] neg_hi:[0,1]
	v_mov_b32_e32 v16, v17
	v_mov_b32_e32 v17, v15
	v_pk_mov_b32 v[18:19], v[10:11], v[18:19] op_sel:[1,0]
	v_mov_b32_e32 v22, v20
	v_pk_add_f32 v[16:17], v[16:17], v[18:19] neg_lo:[0,1] neg_hi:[0,1]
	v_mov_b32_e32 v21, v15
	v_pk_add_f32 v[10:11], v[12:13], v[16:17] neg_lo:[0,1] neg_hi:[0,1]
	s_movk_i32 s3, 0x204
	v_pk_add_f32 v[12:13], v[22:23], v[10:11]
	v_bfe_u32 v40, v192, 4, 4
	v_pk_add_f32 v[16:17], v[12:13], v[12:13] op_sel:[0,1] op_sel_hi:[1,0]
	s_movk_i32 s1, 0x4800
	v_pk_add_f32 v[14:15], v[14:15], v[16:17] op_sel:[1,0] op_sel_hi:[0,1]
	v_mov_b32_e32 v13, v14
	v_pk_add_f32 v[18:19], v[12:13], v[20:21] neg_lo:[0,1] neg_hi:[0,1]
	v_mov_b32_e32 v11, v16
	v_sub_f32_e32 v12, v12, v18
	v_pk_add_f32 v[10:11], v[10:11], v[18:19] neg_lo:[0,1] neg_hi:[0,1]
	v_sub_f32_e32 v12, v20, v12
	v_add_f32_e32 v10, v10, v12
	v_add_f32_e32 v10, v10, v11
	v_add_f32_e32 v11, v14, v10
	v_sub_f32_e32 v12, v11, v14
	v_sub_f32_e32 v10, v10, v12
	v_mul_f32_e32 v12, v24, v11
	v_fma_f32 v11, v24, v11, -v12
	v_fmac_f32_e32 v11, v24, v10
	v_add_f32_e32 v10, v12, v11
	v_cmp_class_f32_e64 s[4:5], v12, s3
	v_sub_f32_e32 v13, v10, v12
	v_sub_f32_e32 v11, v11, v13
	v_cndmask_b32_e64 v10, v10, v12, s[4:5]
	v_mov_b32_e32 v12, 0x37000000
	v_cmp_eq_f32_e64 s[4:5], s7, v10
	v_or_b32_e32 v149, 16, v40
	v_or_b32_e32 v150, 32, v40
	v_cndmask_b32_e64 v12, 0, v12, s[4:5]
	v_sub_f32_e32 v13, v10, v12
	s_mov_b32 s4, 0x3fb8aa3b
	v_mul_f32_e32 v14, 0x3fb8aa3b, v13
	v_fma_f32 v15, v13, s4, -v14
	v_rndne_f32_e32 v16, v14
	v_fmamk_f32 v15, v13, 0x32a5705f, v15
	v_sub_f32_e32 v14, v14, v16
	v_add_f32_e32 v14, v14, v15
	v_exp_f32_e32 v14, v14
	v_cvt_i32_f32_e32 v15, v16
	v_cmp_neq_f32_e64 s[4:5], |v10|, s6
	v_or_b32_e32 v151, 48, v40
	v_mul_u32_u24_e32 v5, 0x4800, v3
; __device__ __forceinline__ void transpose_tile2(const float* tsrc, u16* tdst, int tK, int tN, int tNpad, int tile, u16* sm, const bool rp0 = false, const bool rp1 = false, const bool upperm = false, const float* gk = nullptr) {
;   const int nNt = tNpad >> 6;
;   const int tid = threadIdx.x & 255;
;   const int c4 = tid & 15, r = tid >> 4;
;   float4 v[2][4];
;   int k0s[2], n0s[2];
; #pragma unroll
;   for (int t = 0; t < 2; ++t) {
;     const int kt = (tile + t) / nNt, nt = (tile + t) - kt * nNt;
;     k0s[t] = kt * 64; n0s[t] = nt * 64;
; #pragma unroll
;     for (int i = 0; i < 4; ++i) {
;       const int nsrc0 = upperm ? (((n0s[t] >> 7) & 1) * DFF + 128 * (n0s[t] >> 8) + (n0s[t] & 127)) : n0s[t];
;       const int k = r + 16 * i, n = nsrc0 + c4 * 4;
;       v[t][i] = make_float4(0.f, 0.f, 0.f, 0.f);
;       if (n < tN) v[t][i] = *(const float4*)(tsrc + (size_t)(k0s[t] + k) * tN + n);
;       if (gk) { const float gs = gk[k0s[t] + k]; v[t][i].x *= gs; v[t][i].y *= gs; v[t][i].z *= gs; v[t][i].w *= gs; }
;     }
;   }
; #pragma unroll
;   for (int t = 0; t < 2; ++t)
; #pragma unroll
;     for (int i = 0; i < 4; ++i) {
;       const int k = r + 16 * i;
;       u16* d = sm + t * 64 * LDSP;
;       const uint32_t p01 = pack2(v[t][i].x, v[t][i].y), p23 = pack2(v[t][i].z, v[t][i].w);
;       d[(c4 * 4 + 0) * LDSP + k] = (u16)(p01 & 0xffff);
;       d[(c4 * 4 + 1) * LDSP + k] = (u16)(p01 >> 16);
;       d[(c4 * 4 + 2) * LDSP + k] = (u16)(p23 & 0xffff);
;       d[(c4 * 4 + 3) * LDSP + k] = (u16)(p23 >> 16);
;     }
;   __syncthreads();
;   const int c8 = tid & 7, rn = tid >> 3;
; #pragma unroll
;   for (int t = 0; t < 2; ++t) {
;     const bool ropeperm = t ? rp1 : rp0;
; #pragma unroll
;     for (int i = 0; i < 2; ++i) {
;       const int n = rn + 32 * i;
;       const int nsrc = ropeperm ? (16 * (n >> 5) + (n & 15) + 32 * ((n >> 4) & 1)) : n;
;       const uint4 w = *(const uint4*)(sm + t * 64 * LDSP + nsrc * LDSP + c8 * 8);
; __device__ __forceinline__ void phase_prep(const Params& p, u16* sm) {
;     ...
;       float inv = powf(10000.f, -(float)f / 32.f);
	v_cndmask_b32_e64 v10, 0, v11, s[4:5]
	s_mov_b32 s4, 0xc2ce8ed0
	v_ldexp_f32 v11, v14, v15
	v_cmp_ngt_f32_e64 s[4:5], s4, v13
	v_add_f32_e32 v10, v12, v10
	v_mov_b32_e32 v12, 0x7f800000
	v_cndmask_b32_e64 v11, 0, v11, s[4:5]
	v_cmp_nlt_f32_e64 s[4:5], s7, v13
	v_bfe_u32 v156, v192, 3, 5
	v_and_b32_e32 v7, 63, v192
	v_cndmask_b32_e64 v11, v12, v11, s[4:5]
	v_fma_f32 v10, v11, v10, v11
	v_cmp_class_f32_e64 s[4:5], v11, s3
	v_mov_b32_e32 v38, 0
	v_readlane_b32 s48, v253, 2
	v_cndmask_b32_e64 v10, v10, v11, s[4:5]
	v_cmp_neq_f32_e64 s[4:5], v24, |v24|
	v_mov_b32_e32 v13, v38
	v_lshlrev_b32_e32 v20, 4, v7
	v_cndmask_b32_e64 v11, v12, 0, s[4:5]
	v_cndmask_b32_e64 v11, v11, 1.0, vcc
	v_cmp_class_f32_e64 s[4:5], v24, s3
	v_mov_b32_e32 v21, v38
	v_readlane_b32 s50, v253, 4
	v_cndmask_b32_e64 v147, |v10|, v11, s[4:5]
	v_and_b32_e32 v11, 15, v192
	v_mul_u32_u24_e32 v10, 0x120, v11
	v_or_b32_e32 v12, v40, v10
	v_lshlrev_b32_e32 v12, 1, v12
	v_mad_u32_u24 v152, v3, s1, v12
	v_or_b32_e32 v12, v10, v149
	v_lshlrev_b32_e32 v12, 1, v12
	v_mad_u32_u24 v153, v3, s1, v12
	v_add_lshl_u32 v12, v10, v150, 1
	v_add_lshl_u32 v10, v10, v151, 1
	v_mad_u32_u24 v154, v3, s1, v12
	v_mad_u32_u24 v155, v3, s1, v10
	v_lshlrev_b32_e32 v3, 4, v192
	v_and_b32_e32 v10, 0x70, v3
	v_or_b32_e32 v157, v5, v10
	v_mul_u32_u24_e32 v3, 0x48, v156
	v_lshl_add_u32 v158, v3, 1, v157
	v_lshlrev_b32_e32 v3, 5, v192
	v_and_b32_e32 v3, 0x1800, v3
	v_lshlrev_b32_e32 v12, 8, v40
	v_readlane_b32 s51, v253, 5
	v_readlane_b32 s54, v253, 8
	v_readlane_b32 s55, v253, 9
	v_lshlrev_b32_e32 v42, 2, v11
	s_load_dword s3, s[36:37], 0xb0
	v_or_b32_e32 v163, 0xfc77c000, v3
	v_lshlrev_b32_e32 v14, 8, v149
	v_mov_b32_e32 v15, v38
	v_bfe_i32 v3, v192, 8, 1
	s_movk_i32 s4, 0xb00
	v_lshl_add_u64 v[48:49], s[12:13], 0, v[20:21]
	v_lshlrev_b32_e32 v22, 4, v11
	v_mov_b32_e32 v23, v38
	v_lshl_add_u64 v[54:55], s[16:17], 0, v[20:21]
	v_lshl_add_u64 v[20:21], s[50:51], 0, v[12:13]
	v_lshl_add_u64 v[12:13], s[54:55], 0, v[12:13]
	v_lshlrev_b32_e32 v16, 8, v150
	v_mov_b32_e32 v17, v38
	v_and_or_b32 v164, v3, s4, v42
	v_lshl_add_u64 v[56:57], v[20:21], 0, v[22:23]
	s_mov_b64 s[4:5], 0x4000
	v_lshl_add_u64 v[76:77], v[12:13], 0, v[22:23]
	v_lshl_add_u64 v[12:13], s[54:55], 0, v[14:15]
	v_lshlrev_b32_e32 v18, 8, v151
	v_mov_b32_e32 v19, v38
	v_lshl_add_u64 v[64:65], v[56:57], 0, s[4:5]
	v_lshl_add_u64 v[78:79], v[12:13], 0, v[22:23]
	v_lshl_add_u64 v[12:13], s[54:55], 0, v[16:17]
	v_lshl_add_u64 v[84:85], v[76:77], 0, s[4:5]
	v_readlane_b32 s4, v253, 26
	v_mov_b32_e32 v11, v38
	v_lshl_add_u64 v[80:81], v[12:13], 0, v[22:23]
	v_lshl_add_u64 v[12:13], s[54:55], 0, v[18:19]
	v_readlane_b32 s5, v253, 27
	v_lshl_add_u64 v[82:83], v[12:13], 0, v[22:23]
	v_readlane_b32 s40, v253, 32
	v_lshl_add_u64 v[12:13], s[4:5], 0, v[10:11]
	v_readlane_b32 s4, v253, 22
	s_waitcnt lgkmcnt(0)
; __device__ __forceinline__ void phase_prep(const Params& p, u16* sm) {
;     ...
;   const int n_tr = (768 + 256 + 512 + 256 + 1408 * 2 + 704 * 2 + 64 * 2 + 2 * 2) / 2;
;   const int n_rope = NTOK * 32 / 256;
;   const int n_bias = 64;
;   const int n_norm = NTOK / 8;
;   const int total = n_tr + n_rope + n_bias + n_norm;
;   for (int i = blockIdx.x * NTHR + threadIdx.x; i < 4 * NTOK; i += gridDim.x * NTHR) p.rowss[i] = 0ull;
;   for (int it = 2 * blockIdx.x + sub; it < total; it += 2 * gridDim.x) {
;     if (it < n_tr) {
;       const int tl = it * 2;
;       constexpr int T1 = 768, T2 = T1 + 256, T3 = T2 + 512, T4 = T3 + 256, T5 = T4 + 1408, T6 = T5 + 1408,
;                     T7 = T6 + 704, T8 = T7 + 704, T9 = T8 + 64, T10 = T9 + 64, T11 = T10 + 2;
;       if (tl < T1) { transpose_tile2(p.sba_w_in, p.wt_sba_in, 1024, 3072, 3072, tl - (0), sm); }
;       else if (tl < T2) { transpose_tile2(p.sba_w_out, p.wt_sba_out, 1024, 1024, 1024, tl - (T1), sm); }
;       else if (tl < T3) {
;         const int nt0 = (tl - T2) & 31, nt1 = nt0 + 1;
;         const bool rp0 = (nt0 < 16) || (nt0 == 20) || (nt0 == 21) || (nt0 == 24) || (nt0 == 25);
;         const bool rp1 = (nt1 < 16) || (nt1 == 20) || (nt1 == 21) || (nt1 == 24) || (nt1 == 25);
;         transpose_tile2(p.nsa_w_in, p.wt_nsa_in, 1024, 1840, NSAWP, tl - (T2), sm, rp0, rp1, false, p.norm_mix + DM);
;       }
;       else if (tl < T4) { transpose_tile2(p.nsa_w_out, p.wt_nsa_out, 1024, 1024, 1024, tl - (T3), sm); }
;       else if (tl < T5) { transpose_tile2(p.w_up, p.wt_up0, 1024, NUP, NUP, tl - (T4), sm, false, false, true, p.norm_ffn); }
;       else if (tl < T6) { transpose_tile2(p.w_up + (size_t)1024 * NUP, p.wt_up1, 1024, NUP, NUP, tl - (T5), sm, false, false, true, p.norm_ffn + DM); }
;       else if (tl < T7) { transpose_tile2(p.w_down, p.wt_down0, DFF, 1024, 1024, tl - (T6), sm); }
;       else if (tl < T8) { transpose_tile2(p.w_down + (size_t)DFF * 1024, p.wt_down1, DFF, 1024, 1024, tl - (T7), sm); }
;       else if (tl < T9) { transpose_tile2(p.ck_w1, p.wt_ck1, 2048, 128, 128, tl - (T8), sm); }
;       else if (tl < T10) { transpose_tile2(p.cv_w1, p.wt_cv1, 2048, 128, 128, tl - (T9), sm); }
;       else if (tl < T11) { transpose_tile2(p.ck_w2, p.wt_ck2, 128, 64, 64, tl - (T10), sm); }
;       else { transpose_tile2(p.cv_w2, p.wt_cv2, 128, 64, 64, tl - (T11), sm); }
;     } else if (it < n_tr + n_rope) {
	s_lshl_b32 s1, s3, 1
	v_readlane_b32 s5, v253, 23
	v_readlane_b32 s41, v253, 33
	v_readlane_b32 s42, v253, 34
	v_readlane_b32 s43, v253, 35
	v_readlane_b32 s44, v253, 36
	v_readlane_b32 s45, v253, 37
	v_readlane_b32 s46, v253, 38
	v_readlane_b32 s47, v253, 39
	v_lshl_add_u64 v[96:97], s[4:5], 0, v[10:11]
	s_add_u32 s4, s42, 0xb00000
	v_readlane_b32 s40, v253, 32
	v_readlane_b32 s43, v253, 35
	v_readlane_b32 s30, v253, 24
	s_addc_u32 s5, s43, 0
	v_readlane_b32 s49, v253, 3
	v_readlane_b32 s52, v253, 6
	v_readlane_b32 s53, v253, 7
	v_readlane_b32 s56, v253, 10
	v_readlane_b32 s57, v253, 11
	v_readlane_b32 s58, v253, 12
	v_readlane_b32 s59, v253, 13
	v_readlane_b32 s60, v253, 14
	v_readlane_b32 s61, v253, 15
	v_readlane_b32 s62, v253, 16
	v_readlane_b32 s63, v253, 17
	v_readlane_b32 s31, v253, 25
	v_readlane_b32 s41, v253, 33
	v_readlane_b32 s42, v253, 34
	v_readlane_b32 s44, v253, 36
	v_readlane_b32 s45, v253, 37
	v_readlane_b32 s46, v253, 38
	v_readlane_b32 s47, v253, 39
	v_writelane_b32 v253, s4, 44
	v_lshlrev_b32_e32 v2, 2, v7
	v_or_b32_e32 v4, 0x100, v2
	v_writelane_b32 v253, s5, 45
	v_or_b32_e32 v6, 0x200, v2
	v_readlane_b32 s4, v253, 20
	v_readlane_b32 s5, v253, 21
	v_or_b32_e32 v8, 0x300, v2
	v_lshl_add_u64 v[20:21], s[50:51], 0, v[14:15]
	v_lshl_add_u64 v[100:101], s[4:5], 0, v[10:11]
	v_readlane_b32 s4, v253, 46
	v_readlane_b32 s5, v253, 47
	v_lshlrev_b32_e32 v118, 1, v2
	v_lshrrev_b32_e32 v9, 2, v192
	v_lshl_add_u64 v[102:103], s[4:5], 0, v[10:11]
	s_add_u32 s4, s60, 0x1600000
	s_addc_u32 s5, s61, 0
	s_add_u32 s92, s58, 0x1000
	v_writelane_b32 v253, s4, 48
	s_addc_u32 s93, s59, 0
	s_cmp_lg_u64 s[58:59], 0
	v_writelane_b32 v253, s5, 49
	s_cselect_b64 s[4:5], -1, 0
	v_readlane_b32 s56, v253, 32
	v_readlane_b32 s57, v253, 33
	v_readlane_b32 s58, v253, 34
	v_readlane_b32 s59, v253, 35
	v_readlane_b32 s60, v253, 36
	v_readlane_b32 s61, v253, 37
	v_readlane_b32 s62, v253, 38
	v_readlane_b32 s63, v253, 39
	v_writelane_b32 v253, s4, 50
	v_lshl_add_u64 v[58:59], v[20:21], 0, v[22:23]
	v_lshl_add_u64 v[20:21], s[50:51], 0, v[16:17]
	v_writelane_b32 v253, s5, 51
	v_mbcnt_lo_u32_b32 v2, -1, 0
	v_and_b32_e32 v47, 0x7f, v192
	v_and_b32_e32 v127, 32, v9
	v_or_b32_e32 v159, 32, v156
	v_lshl_add_u64 v[60:61], v[20:21], 0, v[22:23]
	v_lshl_add_u64 v[20:21], s[50:51], 0, v[18:19]
	v_readlane_b32 s4, v253, 18
	v_mbcnt_hi_u32_b32 v168, -1, v2
	s_mov_b32 s0, 0xfff3fe00
	s_movk_i32 s34, 0x80
	v_lshlrev_b32_e32 v9, 2, v47
	v_and_or_b32 v161, v156, 15, v127
	v_lshl_add_u64 v[62:63], v[20:21], 0, v[22:23]
	s_mov_b64 s[6:7], 0x5000
	s_mov_b64 s[8:9], 0x6000
	s_mov_b64 s[28:29], 0x7000
	v_lshl_add_u64 v[20:21], s[30:31], 0, v[10:11]
	v_lshlrev_b32_e32 v24, 8, v156
	v_mov_b32_e32 v25, v38
	v_lshlrev_b32_e32 v26, 8, v159
	v_mov_b32_e32 v27, v38
	v_readlane_b32 s5, v253, 19
	s_add_u32 s16, s16, 0x1000
	v_mov_b32_e32 v3, 0xfff8ff80
	v_and_b32_e32 v2, 64, v168
	v_or_b32_sdwa v45, v192, s0 dst_sel:DWORD dst_unused:UNUSED_PAD src0_sel:BYTE_0 src1_sel:DWORD
	v_or_b32_e32 v145, v5, v9
	v_mov_b32_e32 v43, v38
	v_lshlrev_b32_e32 v44, 11, v156
	v_lshlrev_b32_e32 v46, 11, v159
	v_or_b32_e32 v160, 64, v42
	v_or_b32_e32 v162, 16, v161
	v_lshl_add_u64 v[50:51], s[52:53], 0, v[22:23]
	v_lshl_add_u64 v[52:53], s[48:49], 0, v[22:23]
	v_lshl_add_u64 v[66:67], v[56:57], 0, s[6:7]
	v_lshl_add_u64 v[68:69], v[56:57], 0, s[8:9]
	v_lshl_add_u64 v[70:71], v[56:57], 0, s[28:29]
	v_lshl_add_u64 v[72:73], v[20:21], 0, v[24:25]
	v_lshl_add_u64 v[74:75], v[20:21], 0, v[26:27]
	v_lshl_add_u64 v[86:87], v[76:77], 0, s[6:7]
	v_lshl_add_u64 v[88:89], v[76:77], 0, s[8:9]
	v_lshl_add_u64 v[90:91], v[76:77], 0, s[28:29]
	v_lshl_add_u64 v[92:93], v[12:13], 0, v[24:25]
	v_lshl_add_u64 v[94:95], v[12:13], 0, v[26:27]
	v_lshl_add_u64 v[98:99], s[82:83], 0, v[10:11]
	v_lshl_add_u64 v[104:105], s[68:69], 0, v[10:11]
	v_lshl_add_u64 v[106:107], s[4:5], 0, v[10:11]
	v_lshl_add_u64 v[108:109], s[70:71], 0, v[10:11]
	s_addc_u32 s17, s17, 0
	v_lshl_add_u64 v[110:111], s[90:91], 0, v[10:11]
	v_lshl_add_u64 v[112:113], s[88:89], 0, v[10:11]
	v_lshl_add_u64 v[114:115], s[72:73], 0, v[10:11]
	v_mov_b32_e32 v41, v38
	v_lshl_add_u32 v165, v1, 6, v3
	s_lshl_b32 s3, s3, 7
	v_or_b32_e32 v116, 0x800, v9
	v_mov_b32_e32 v117, v38
	s_movk_i32 s28, 0xc01
	v_lshlrev_b32_e32 v120, 1, v4
	v_lshlrev_b32_e32 v122, 1, v6
	v_lshlrev_b32_e32 v124, 1, v8
	s_mov_b32 s31, 0x3c439041
	s_mov_b32 s33, 0xdb629599
	s_mov_b32 s42, 0xf534ddc0
	s_mov_b32 s43, 0xfc2757d1
	s_mov_b32 s44, 0x4e441529
	v_mov_b32_e32 v166, 0x3c0881c4
	v_mov_b32_e32 v167, 0xbab64f3b
	v_add_u32_e32 v169, 64, v2
	v_xor_b32_e32 v170, 32, v168
	v_xor_b32_e32 v171, 16, v168
	v_xor_b32_e32 v172, 8, v168
	v_xor_b32_e32 v173, 4, v168
	v_xor_b32_e32 v174, 2, v168
	v_xor_b32_e32 v175, 1, v168
	v_mov_b32_e32 v126, 0x358637bd
	v_not_b32_e32 v176, 63
	v_not_b32_e32 v177, 31
	v_mov_b32_e32 v178, 0x7fc00000
	v_mov_b32_e32 v179, 0xfffd0800
	v_mov_b32_e32 v180, 0xfffd1000
	s_mov_b32 s45, 0xa2f9836e
	s_mov_b32 s0, 0x3fc90fda
	s_mov_b32 s85, 0xbfc90fda
	s_movk_i32 s84, 0x400
	s_movk_i32 s30, 0x1600
	s_movk_i32 s29, 0x730
	s_mov_b32 s78, 0x2aaaaaab
	s_movk_i32 s79, 0xffd0
	s_movk_i32 s80, 0xc00
	s_movk_i32 s81, 0x3000
	v_cmp_lt_u32_sdwa s[96:97], v192, s34 src0_sel:BYTE_0 src1_sel:DWORD
	s_mov_b64 s[46:47], 0
	s_branch .LBB0_12
	s_nop 0
